# v024 stack + MLA loop: persistent -m splat as MFMA C operand (drops 16 VALU per MLA tile) and first K fragment reads hoisted behind the barrier
# speedup vs baseline: 1.0052x; 1.0016x over previous
.LBB0_169:
	s_and_b32 s0, s64, 31
	s_lshl_b32 s0, s0, 6
	s_or_b32 s14, s14, s0
	s_mul_i32 s0, s15, 0x600
	s_mul_hi_u32 s1, s14, 0x600
	s_add_i32 s1, s1, s0
	s_mul_i32 s0, s14, 0x600
	s_add_u32 s0, s38, s0
	s_addc_u32 s1, s39, s1
	s_mul_hi_i32 s3, s2, 0xc0000
	s_mul_i32 s2, s2, 0xc0000
	v_mov_b32_e32 v158, v218
	s_add_u32 s4, s28, s2
	v_mov_b32_e32 v4, v218
	s_addc_u32 s5, s29, s3
	s_add_i32 s3, 0, 0x14000
	v_and_b32_e32 v0, 0x3fffffc0, v4
	v_lshl_add_u32 v159, v0, 2, s3
	v_ashrrev_i32_e32 v0, 6, v4
	v_and_b32_e32 v6, 31, v4
	v_readfirstlane_b32 s3, v0
	v_lshlrev_b32_e32 v0, 5, v0
	v_and_or_b32 v0, v0, 32, v6
	v_mul_u32_u24_e32 v0, 0x300, v0
	v_ashrrev_i32_e32 v2, 7, v4
	v_lshlrev_b32_e32 v184, 1, v0
	v_mul_lo_u32 v2, v2, s60
	v_lshl_add_u64 v[0:1], s[0:1], 0, v[184:185]
	v_ashrrev_i32_e32 v3, 31, v2
	v_lshl_add_u64 v[0:1], v[2:3], 1, v[0:1]
	v_lshrrev_b32_e32 v2, 1, v4
	v_and_b32_e32 v5, 63, v4
	v_and_b32_e32 v184, 16, v2
	v_lshl_add_u64 v[0:1], v[0:1], 0, v[184:185]
	s_lshl_b32 s6, s3, 10
	v_lshlrev_b32_e32 v3, 4, v5
	global_load_dwordx4 v[96:99], v[0:1], off
	global_load_dwordx4 v[100:103], v[0:1], off offset:32
	global_load_dwordx4 v[104:107], v[0:1], off offset:64
	global_load_dwordx4 v[108:111], v[0:1], off offset:96
	global_load_dwordx4 v[112:115], v[0:1], off offset:128
	global_load_dwordx4 v[116:119], v[0:1], off offset:160
	global_load_dwordx4 v[120:123], v[0:1], off offset:192
	global_load_dwordx4 v[124:127], v[0:1], off offset:224
	global_load_dwordx4 v[128:131], v[0:1], off offset:256
	global_load_dwordx4 v[132:135], v[0:1], off offset:288
	global_load_dwordx4 v[136:139], v[0:1], off offset:320
	global_load_dwordx4 v[140:143], v[0:1], off offset:352
	v_or_b32_e32 v0, s6, v3
	s_mov_b32 s0, 0x2aaaaaab
	v_mul_hi_i32 v1, v0, s0
	v_lshrrev_b32_e32 v7, 31, v1
	v_ashrrev_i32_e32 v1, 6, v1
	v_add_u32_e32 v1, v1, v7
	v_mul_i32_i24_e32 v7, 0x180, v1
	v_sub_u32_e32 v7, v0, v7
	v_ashrrev_i32_e32 v7, 4, v7
	v_lshrrev_b32_e32 v8, 1, v1
	v_bitop3_b32 v7, v8, v7, 7 bitop3:0x6c
	v_mul_i32_i24_e32 v1, 0xc0, v1
	v_lshl_add_u32 v146, v7, 3, v1
	v_add_u32_e32 v1, 0x2000, v0
	v_mul_hi_i32 v7, v1, s0
	v_lshrrev_b32_e32 v8, 31, v7
	v_ashrrev_i32_e32 v7, 6, v7
	v_add_u32_e32 v7, v7, v8
	v_mul_i32_i24_e32 v8, 0x180, v7
	v_sub_u32_e32 v1, v1, v8
	v_ashrrev_i32_e32 v1, 4, v1
	v_lshrrev_b32_e32 v8, 1, v7
	v_bitop3_b32 v1, v8, v1, 7 bitop3:0x6c
	v_mul_i32_i24_e32 v7, 0xc0, v7
	v_add_u32_e32 v0, 0x4000, v0
	v_lshl_add_u32 v148, v1, 3, v7
	v_mul_hi_i32 v1, v0, s0
	v_lshrrev_b32_e32 v7, 31, v1
	v_ashrrev_i32_e32 v1, 6, v1
	v_add_u32_e32 v1, v1, v7
	v_mul_i32_i24_e32 v7, 0x180, v1
	v_sub_u32_e32 v0, v0, v7
	v_ashrrev_i32_e32 v0, 4, v0
	v_lshrrev_b32_e32 v7, 1, v1
	v_bitop3_b32 v0, v7, v0, 7 bitop3:0x6c
	v_mul_i32_i24_e32 v1, 0xc0, v1
	v_lshlrev_b32_e32 v7, 3, v5
	s_lshl_b32 s0, s3, 6
	v_lshl_add_u32 v150, v0, 3, v1
	v_and_b32_e32 v1, 32, v4
	s_and_b32 s0, s0, 64
	v_and_b32_e32 v8, 24, v7
	v_or3_b32 v1, v8, v1, s0
	s_ashr_i32 s0, s6, 8
	s_and_b32 s1, s0, 0xfffff0
	s_lshr_b32 s0, s0, 1
	v_bfe_u32 v0, v4, 2, 2
	s_and_b32 s0, s0, 4
	v_and_or_b32 v0, v2, 8, v0
	s_or_b32 s0, s1, s0
	v_or_b32_e32 v8, s0, v0
	s_add_i32 s0, s6, 0x2000
	s_ashr_i32 s0, s0, 8
	s_lshl_b32 s2, s64, 2
	s_and_b32 s1, s0, 0xfffff0
	s_lshr_b32 s0, s0, 1
	s_and_b32 s2, s2, 28
	s_and_b32 s0, s0, 4
	s_or_b32 s0, s1, s0
	s_mulk_i32 s2, 0x6000
	v_or_b32_e32 v0, s0, v0
	s_add_u32 s0, s4, s2
	s_addc_u32 s1, s5, 0
	s_add_i32 s30, s6, 0
	v_ashrrev_i32_e32 v147, 31, v146
	v_mad_i32_i24 v152, v8, s60, v1
	v_mad_i32_i24 v154, v0, s60, v1
	s_add_i32 m0, s30, 0x8000
	v_lshl_add_u64 v[0:1], v[146:147], 1, s[0:1]
	v_ashrrev_i32_e32 v149, 31, v148
	s_waitcnt lgkmcnt(0)
	s_barrier
	global_load_lds_dwordx4 v[0:1], off
	v_lshl_add_u64 v[0:1], v[148:149], 1, s[0:1]
	s_add_i32 m0, s30, 0xa000
	v_ashrrev_i32_e32 v151, 31, v150
	global_load_lds_dwordx4 v[0:1], off
	v_lshl_add_u64 v[0:1], v[150:151], 1, s[0:1]
	s_add_i32 m0, s30, 0xc000
	v_ashrrev_i32_e32 v153, 31, v152
	global_load_lds_dwordx4 v[0:1], off
	v_lshl_add_u64 v[0:1], v[152:153], 1, s[0:1]
	s_mov_b32 m0, s30
	v_ashrrev_i32_e32 v155, 31, v154
	global_load_lds_dwordx4 v[0:1], off
	v_lshl_add_u64 v[0:1], v[154:155], 1, s[0:1]
	s_add_i32 m0, s30, 0x2000
	s_cmp_lg_u32 0, -1
	global_load_lds_dwordx4 v[0:1], off
	s_cselect_b32 s0, 0, 0
	s_add_i32 s1, s0, 0x8000
	v_lshlrev_b32_e32 v8, 1, v4
	v_lshlrev_b32_e32 v1, 3, v4
	v_mov_b32_e32 v4, s1
	s_movk_i32 s1, 0x180
	v_and_b32_e32 v1, 0x70, v1
	v_mad_u32_u24 v161, v6, s1, v4
	s_movk_i32 s1, 0x60
	v_and_b32_e32 v0, 32, v8
	v_bitop3_b32 v165, v184, v1, s1 bitop3:0x36
	s_movk_i32 s1, 0x118
	v_and_b32_e32 v3, 0xc0, v3
	v_and_or_b32 v0, v7, s1, v0
	v_add3_u32 v166, v3, s0, v0
	s_and_b32 s0, s64, 7
	v_mov_b32_e32 v14, v185
	v_mov_b32_e32 v15, v185
	v_bitop3_b32 v162, v2, v1, 16 bitop3:0x6c
	v_bitop3_b32 v163, v184, v1, 32 bitop3:0x36
	v_bitop3_b32 v164, v184, v1, 64 bitop3:0x36
	v_cmp_gt_u32_e64 s[6:7], 32, v5
	v_lshl_add_u32 v160, v6, 2, v159
	s_lshl_b32 s0, s0, 8
	v_mov_b32_e32 v0, v185
	v_mov_b32_e32 v1, v185
	v_mov_b32_e32 v2, v185
	v_mov_b32_e32 v3, v185
	v_mov_b32_e32 v4, v185
	v_mov_b32_e32 v5, v185
	v_mov_b32_e32 v6, v185
	v_mov_b32_e32 v7, v185
	v_mov_b32_e32 v8, v185
	v_mov_b32_e32 v9, v185
	v_mov_b32_e32 v10, v185
	v_mov_b32_e32 v11, v185
	v_mov_b32_e32 v12, v185
	v_mov_b32_e32 v13, v185
	v_mov_b64_e32 v[30:31], v[14:15]
	v_mov_b64_e32 v[46:47], v[14:15]
	v_mov_b64_e32 v[62:63], v[14:15]
	s_mov_b32 s31, 0
	s_or_b32 s34, s0, 64
	v_lshlrev_b32_e32 v212, 1, v146
	v_lshlrev_b32_e32 v213, 1, v148
	v_lshlrev_b32_e32 v214, 1, v150
	v_lshlrev_b32_e32 v215, 1, v152
	v_lshlrev_b32_e32 v216, 1, v154
	v_mov_b32_e32 v167, 0
	v_mov_b32_e32 v196, 0x80000000
	v_mov_b32_e32 v197, 0x80000000
	v_mov_b32_e32 v198, 0x80000000
	v_mov_b32_e32 v199, 0x80000000
	v_mov_b32_e32 v200, 0x80000000
	v_mov_b32_e32 v201, 0x80000000
	v_mov_b32_e32 v202, 0x80000000
	v_mov_b32_e32 v203, 0x80000000
	v_mov_b32_e32 v204, 0x80000000
	v_mov_b32_e32 v205, 0x80000000
	v_mov_b32_e32 v206, 0x80000000
	v_mov_b32_e32 v207, 0x80000000
	v_mov_b32_e32 v208, 0x80000000
	v_mov_b32_e32 v209, 0x80000000
	v_mov_b32_e32 v210, 0x80000000
	v_mov_b32_e32 v211, 0x80000000
	v_mov_b64_e32 v[28:29], v[12:13]
	v_mov_b64_e32 v[26:27], v[10:11]
	v_mov_b64_e32 v[24:25], v[8:9]
	v_mov_b64_e32 v[22:23], v[6:7]
	v_mov_b64_e32 v[20:21], v[4:5]
	v_mov_b64_e32 v[18:19], v[2:3]
	v_mov_b64_e32 v[16:17], v[0:1]
	v_mov_b64_e32 v[44:45], v[12:13]
	v_mov_b64_e32 v[42:43], v[10:11]
	v_mov_b64_e32 v[40:41], v[8:9]
	v_mov_b64_e32 v[38:39], v[6:7]
	v_mov_b64_e32 v[36:37], v[4:5]
	v_mov_b64_e32 v[34:35], v[2:3]
	v_mov_b64_e32 v[32:33], v[0:1]
	v_mov_b64_e32 v[60:61], v[12:13]
	v_mov_b64_e32 v[58:59], v[10:11]
	v_mov_b64_e32 v[56:57], v[8:9]
	v_mov_b64_e32 v[54:55], v[6:7]
	v_mov_b64_e32 v[52:53], v[4:5]
	v_mov_b64_e32 v[50:51], v[2:3]
	v_mov_b64_e32 v[48:49], v[0:1]
	v_mov_b32_e32 v168, 0
	s_waitcnt vmcnt(0) lgkmcnt(0)
	s_barrier
	s_and_b32 s35, s31, 1
	v_add_u32_e32 v156, v161, v162
	ds_read_b128 v[236:239], v156 offset:0
	ds_read_b128 v[240:243], v156 offset:0x3000
	s_cmp_eq_u32 s31, 31
	s_cbranch_scc1 .LBB0_171
.LBB0_170:
	s_and_b32 s0, s34, 0x7c0
	s_mulk_i32 s0, 0x180
	s_add_u32 s0, s4, s0
	s_addc_u32 s1, s5, 0
	s_xor_b32 s2, s35, 1
	s_mulk_i32 s2, 0x6000
	s_add_i32 s2, s30, s2
	s_add_i32 m0, s2, 0x8000
	s_nop 0
	global_load_lds_dwordx4 v212, s[0:1]
	s_add_i32 m0, s2, 0xa000
	s_nop 0
	global_load_lds_dwordx4 v213, s[0:1]
	s_add_i32 m0, s2, 0xc000
	s_lshl_b32 s2, s35, 14
	s_xor_b32 s2, s2, 0x4000
	s_add_i32 s2, s30, s2
	global_load_lds_dwordx4 v214, s[0:1]
	s_mov_b32 m0, s2
	s_nop 0
	global_load_lds_dwordx4 v215, s[0:1]
	s_add_i32 m0, s2, 0x2000
	s_nop 0
	global_load_lds_dwordx4 v216, s[0:1]
.LBB0_171:
	s_mul_i32 s0, s35, 0x6000
	v_add_u32_e32 v80, s0, v161
	v_add_u32_e32 v169, v80, v163
	ds_read_b128 v[178:181], v169 offset:0
	ds_read_b128 v[190:193], v169 offset:0x3000
	s_waitcnt lgkmcnt(2)
	v_add_u32_e32 v182, v80, v164
	v_add_u32_e32 v183, v80, v165
	v_mfma_f32_32x32x16_bf16 v[80:95], v[236:239], v[96:99], v[196:211]
	ds_read_b128 v[170:173], v182 offset:0
	v_mfma_f32_32x32x16_bf16 v[64:79], v[240:243], v[96:99], v[196:211]
	ds_read_b128 v[174:177], v182 offset:0x3000
	s_waitcnt lgkmcnt(2)
	v_mfma_f32_32x32x16_bf16 v[80:95], v[178:181], v[100:103], v[80:95]
	ds_read_b128 v[178:181], v183 offset:0
	v_mfma_f32_32x32x16_bf16 v[64:79], v[190:193], v[100:103], v[64:79]
	ds_read_b128 v[190:193], v183 offset:0x3000
	s_waitcnt lgkmcnt(2)
	v_mfma_f32_32x32x16_bf16 v[80:95], v[170:173], v[104:107], v[80:95]
	ds_read_b128 v[170:173], v156 offset:0x80
	v_mfma_f32_32x32x16_bf16 v[64:79], v[174:177], v[104:107], v[64:79]
	ds_read_b128 v[174:177], v156 offset:0x3080
	s_waitcnt lgkmcnt(2)
	v_mfma_f32_32x32x16_bf16 v[80:95], v[178:181], v[108:111], v[80:95]
	ds_read_b128 v[178:181], v169 offset:0x80
	v_mfma_f32_32x32x16_bf16 v[64:79], v[190:193], v[108:111], v[64:79]
	ds_read_b128 v[190:193], v169 offset:0x3080
	s_waitcnt lgkmcnt(2)
	v_mfma_f32_32x32x16_bf16 v[80:95], v[170:173], v[112:115], v[80:95]
	ds_read_b128 v[170:173], v182 offset:0x80
	v_mfma_f32_32x32x16_bf16 v[64:79], v[174:177], v[112:115], v[64:79]
	ds_read_b128 v[174:177], v182 offset:0x3080
	s_waitcnt lgkmcnt(2)
	v_mfma_f32_32x32x16_bf16 v[80:95], v[178:181], v[116:119], v[80:95]
	ds_read_b128 v[178:181], v183 offset:0x80
	v_mfma_f32_32x32x16_bf16 v[64:79], v[190:193], v[116:119], v[64:79]
	ds_read_b128 v[190:193], v183 offset:0x3080
	s_waitcnt lgkmcnt(2)
	v_mfma_f32_32x32x16_bf16 v[80:95], v[170:173], v[120:123], v[80:95]
	ds_read_b128 v[170:173], v156 offset:0x100
	v_mfma_f32_32x32x16_bf16 v[64:79], v[174:177], v[120:123], v[64:79]
	ds_read_b128 v[174:177], v156 offset:0x3100
	s_waitcnt lgkmcnt(2)
	v_mfma_f32_32x32x16_bf16 v[80:95], v[178:181], v[124:127], v[80:95]
	ds_read_b128 v[178:181], v169 offset:0x100
	v_mfma_f32_32x32x16_bf16 v[64:79], v[190:193], v[124:127], v[64:79]
	ds_read_b128 v[190:193], v169 offset:0x3100
	s_waitcnt lgkmcnt(2)
	v_mfma_f32_32x32x16_bf16 v[80:95], v[170:173], v[128:131], v[80:95]
	ds_read_b128 v[170:173], v182 offset:0x100
	v_mfma_f32_32x32x16_bf16 v[64:79], v[174:177], v[128:131], v[64:79]
	ds_read_b128 v[174:177], v182 offset:0x3100
	s_waitcnt lgkmcnt(2)
	v_mfma_f32_32x32x16_bf16 v[80:95], v[178:181], v[132:135], v[80:95]
	ds_read_b128 v[178:181], v183 offset:0x100
	v_mfma_f32_32x32x16_bf16 v[64:79], v[190:193], v[132:135], v[64:79]
	ds_read_b128 v[190:193], v183 offset:0x3100
	s_waitcnt lgkmcnt(2)
	v_mfma_f32_32x32x16_bf16 v[80:95], v[170:173], v[136:139], v[80:95]
	s_waitcnt lgkmcnt(0)
	v_mfma_f32_32x32x16_bf16 v[64:79], v[174:177], v[136:139], v[64:79]
	v_mfma_f32_32x32x16_bf16 v[80:95], v[178:181], v[140:143], v[80:95]
	s_cmp_eq_u32 s31, 0
	s_cselect_b64 s[2:3], -1, 0
	s_cmp_lg_u32 s31, 0
	v_mfma_f32_32x32x16_bf16 v[64:79], v[190:193], v[140:143], v[64:79]
	s_nop 7
	v_max_f32_e32 v156, v80, v81
	v_max3_f32 v156, v156, v82, v83
	v_max3_f32 v156, v156, v84, v85
	v_max3_f32 v156, v156, v86, v87
	v_max3_f32 v156, v156, v88, v89
	v_max3_f32 v156, v156, v90, v91
	v_max3_f32 v156, v156, v92, v93
	v_max3_f32 v156, v156, v94, v95
	v_max3_f32 v156, v156, v64, v65
	v_max3_f32 v156, v156, v66, v67
	v_max3_f32 v156, v156, v68, v69
	v_max3_f32 v156, v156, v70, v71
	v_max3_f32 v156, v156, v72, v73
	v_max3_f32 v156, v156, v74, v75
	v_max3_f32 v156, v156, v76, v77
	v_max3_f32 v156, v156, v78, v79
	s_cbranch_scc0 .Lmx3_first
	v_cmp_ge_f32_e32 vcc, s62, v156
	s_cmp_lg_u64 vcc, exec
	s_mov_b64 s[24:25], 0
	s_mov_b64 s[22:23], 0
	s_cbranch_scc1 .Lmx3_slow
	v_mov_b32_e32 v169, 1.0
	s_branch .LBB0_183

.LBB0_179:
	v_exp_f32_e64 v169, -v156
	v_add_f32_e32 v167, v167, v156
	v_xor_b32_e32 v196, 0x80000000, v167
	v_mov_b32_e32 v197, v196
	v_mov_b32_e32 v198, v196
	v_mov_b32_e32 v199, v196
	v_mov_b32_e32 v200, v196
	v_mov_b32_e32 v201, v196
	v_mov_b32_e32 v202, v196
	v_mov_b32_e32 v203, v196
	v_mov_b32_e32 v204, v196
	v_mov_b32_e32 v205, v196
	v_mov_b32_e32 v206, v196
	v_mov_b32_e32 v207, v196
	v_mov_b32_e32 v208, v196
	v_mov_b32_e32 v209, v196
	v_mov_b32_e32 v210, v196
	v_mov_b32_e32 v211, v196
	v_pk_add_f32 v[80:81], v[80:81], v[156:157] op_sel_hi:[1,0] neg_lo:[0,1] neg_hi:[0,1]
	v_pk_add_f32 v[82:83], v[82:83], v[156:157] op_sel_hi:[1,0] neg_lo:[0,1] neg_hi:[0,1]
	v_cndmask_b32_e64 v169, v169, 0, s[2:3]
	v_pk_add_f32 v[84:85], v[84:85], v[156:157] op_sel_hi:[1,0] neg_lo:[0,1] neg_hi:[0,1]
	v_pk_add_f32 v[86:87], v[86:87], v[156:157] op_sel_hi:[1,0] neg_lo:[0,1] neg_hi:[0,1]
	v_pk_add_f32 v[88:89], v[88:89], v[156:157] op_sel_hi:[1,0] neg_lo:[0,1] neg_hi:[0,1]
	v_pk_add_f32 v[90:91], v[90:91], v[156:157] op_sel_hi:[1,0] neg_lo:[0,1] neg_hi:[0,1]
	v_pk_add_f32 v[92:93], v[92:93], v[156:157] op_sel_hi:[1,0] neg_lo:[0,1] neg_hi:[0,1]
	v_pk_add_f32 v[94:95], v[94:95], v[156:157] op_sel_hi:[1,0] neg_lo:[0,1] neg_hi:[0,1]
	v_sub_f32_e32 v79, v79, v156
	v_sub_f32_e32 v78, v78, v156
	v_sub_f32_e32 v77, v77, v156
	v_sub_f32_e32 v76, v76, v156
	v_sub_f32_e32 v75, v75, v156
	v_sub_f32_e32 v74, v74, v156
	v_sub_f32_e32 v73, v73, v156
	v_sub_f32_e32 v72, v72, v156
	v_sub_f32_e32 v71, v71, v156
	v_sub_f32_e32 v70, v70, v156
	v_sub_f32_e32 v69, v69, v156
	v_sub_f32_e32 v68, v68, v156
	v_sub_f32_e32 v67, v67, v156
	v_sub_f32_e32 v66, v66, v156
	v_sub_f32_e32 v65, v65, v156
	v_sub_f32_e32 v64, v64, v156
	s_and_b64 vcc, exec, s[2:3]
	s_cbranch_vccnz .LBB0_183
	v_cmp_gt_f32_e32 vcc, 1.0, v169
	s_cbranch_vccz .LBB0_183

.LBB0_183:
	v_exp_f32_e32 v80, v80
	v_exp_f32_e32 v81, v81
	v_exp_f32_e32 v82, v82
	v_exp_f32_e32 v83, v83
	v_exp_f32_e32 v84, v84
	v_exp_f32_e32 v156, v64
	v_exp_f32_e32 v85, v85
	v_add_f32_e32 v64, v81, v80
	v_exp_f32_e32 v86, v86
	v_add_f32_e32 v64, v82, v64
	v_exp_f32_e32 v87, v87
	v_add_f32_e32 v64, v83, v64
	v_exp_f32_e32 v88, v88
	v_add_f32_e32 v64, v84, v64
	v_exp_f32_e32 v89, v89
	v_add_f32_e32 v64, v85, v64
	v_exp_f32_e32 v90, v90
	v_add_f32_e32 v64, v86, v64
	v_exp_f32_e32 v91, v91
	v_add_f32_e32 v64, v87, v64
	v_exp_f32_e32 v92, v92
	v_add_f32_e32 v64, v88, v64
	v_exp_f32_e32 v93, v93
	v_add_f32_e32 v64, v89, v64
	v_exp_f32_e32 v94, v94
	v_add_f32_e32 v64, v90, v64
	v_exp_f32_e32 v95, v95
	v_add_f32_e32 v64, v91, v64
	v_add_f32_e32 v64, v92, v64
	v_exp_f32_e32 v65, v65
	v_add_f32_e32 v64, v93, v64
	v_exp_f32_e32 v170, v66
	v_add_f32_e32 v64, v94, v64
	v_exp_f32_e32 v171, v67
	v_add_f32_e32 v64, v95, v64
	v_exp_f32_e32 v172, v68
	v_add_f32_e32 v64, v156, v64
	v_exp_f32_e32 v173, v69
	v_add_f32_e32 v64, v65, v64
	v_exp_f32_e32 v174, v70
	v_add_f32_e32 v64, v170, v64
	v_exp_f32_e32 v175, v71
	v_add_f32_e32 v64, v171, v64
	v_exp_f32_e32 v176, v72
	v_add_f32_e32 v64, v172, v64
	v_exp_f32_e32 v177, v73
	v_add_f32_e32 v64, v173, v64
	v_exp_f32_e32 v178, v74
	v_add_f32_e32 v64, v174, v64
	v_exp_f32_e32 v179, v75
	v_add_f32_e32 v64, v175, v64
	v_exp_f32_e32 v180, v76
	v_add_f32_e32 v64, v176, v64
	v_exp_f32_e32 v181, v77
	v_add_f32_e32 v64, v177, v64
	v_exp_f32_e32 v182, v78
	v_add_f32_e32 v64, v178, v64
	v_exp_f32_e32 v183, v79
	v_add_f32_e32 v64, v179, v64
	v_add_f32_e32 v64, v180, v64
	v_add_f32_e32 v64, v181, v64
	v_add_f32_e32 v64, v182, v64
	v_add_f32_e32 v64, v183, v64
	s_add_i32 s31, s31, 1
	v_fmac_f32_e32 v64, v168, v169
	v_cvt_pk_bf16_f32 v66, v80, v81
	v_cvt_pk_bf16_f32 v67, v82, v83
	v_cvt_pk_bf16_f32 v68, v84, v85
	v_cvt_pk_bf16_f32 v69, v86, v87
	v_cvt_pk_bf16_f32 v70, v88, v89
	v_cvt_pk_bf16_f32 v71, v90, v91
	v_cvt_pk_bf16_f32 v72, v92, v93
	v_cvt_pk_bf16_f32 v73, v94, v95
	v_cvt_pk_bf16_f32 v74, v156, v65
	v_cvt_pk_bf16_f32 v75, v170, v171
	v_cvt_pk_bf16_f32 v76, v172, v173
	v_cvt_pk_bf16_f32 v77, v174, v175
	v_cvt_pk_bf16_f32 v78, v176, v177
	v_cvt_pk_bf16_f32 v79, v178, v179
	v_cvt_pk_bf16_f32 v80, v180, v181
	v_cvt_pk_bf16_f32 v81, v182, v183
	s_nop 0
	v_permlane32_swap_b32_e32 v66, v68
	v_permlane32_swap_b32_e32 v67, v69
	v_permlane32_swap_b32_e32 v70, v72
	v_permlane32_swap_b32_e32 v71, v73
	v_permlane32_swap_b32_e32 v74, v76
	v_permlane32_swap_b32_e32 v75, v77
	v_permlane32_swap_b32_e32 v78, v80
	v_permlane32_swap_b32_e32 v79, v81
	v_lshl_add_u32 v65, s35, 14, v166
	ds_read_b64_tr_b16 v[82:83], v65 offset:0
	ds_read_b64_tr_b16 v[84:85], v65 offset:0x800
	ds_read_b64_tr_b16 v[86:87], v65 offset:0x1000
	ds_read_b64_tr_b16 v[88:89], v65 offset:0x1800
	ds_read_b64_tr_b16 v[90:91], v65 offset:0x2000
	ds_read_b64_tr_b16 v[92:93], v65 offset:0x2800
	ds_read_b64_tr_b16 v[168:169], v65 offset:0x3000
	ds_read_b64_tr_b16 v[170:171], v65 offset:0x3800
	ds_read_b64_tr_b16 v[172:173], v65 offset:0x200
	ds_read_b64_tr_b16 v[174:175], v65 offset:0xa00
	ds_read_b64_tr_b16 v[176:177], v65 offset:0x1200
	ds_read_b64_tr_b16 v[178:179], v65 offset:0x1a00
	ds_read_b64_tr_b16 v[180:181], v65 offset:0x2200
	ds_read_b64_tr_b16 v[182:183], v65 offset:0x2a00
	ds_read_b64_tr_b16 v[190:191], v65 offset:0x3200
	ds_read_b64_tr_b16 v[192:193], v65 offset:0x3a00
	s_waitcnt lgkmcnt(8)
	s_nop 0
	v_mfma_f32_32x32x16_bf16 v[48:63], v[66:69], v[82:85], v[48:63]
	ds_read_b64_tr_b16 v[82:83], v65 offset:0x400
	ds_read_b64_tr_b16 v[84:85], v65 offset:0xc00
	v_mfma_f32_32x32x16_bf16 v[48:63], v[70:73], v[86:89], v[48:63]
	ds_read_b64_tr_b16 v[86:87], v65 offset:0x1400
	ds_read_b64_tr_b16 v[88:89], v65 offset:0x1c00
	v_mfma_f32_32x32x16_bf16 v[48:63], v[74:77], v[90:93], v[48:63]
	ds_read_b64_tr_b16 v[90:91], v65 offset:0x2400
	ds_read_b64_tr_b16 v[92:93], v65 offset:0x2c00
	v_mfma_f32_32x32x16_bf16 v[48:63], v[78:81], v[168:171], v[48:63]
	ds_read_b64_tr_b16 v[168:169], v65 offset:0x3400
	ds_read_b64_tr_b16 v[170:171], v65 offset:0x3c00
	s_waitcnt lgkmcnt(8)
	v_mfma_f32_32x32x16_bf16 v[32:47], v[66:69], v[172:175], v[32:47]
	ds_read_b64_tr_b16 v[172:173], v65 offset:0x600
	ds_read_b64_tr_b16 v[174:175], v65 offset:0xe00
	v_mfma_f32_32x32x16_bf16 v[32:47], v[70:73], v[176:179], v[32:47]
	ds_read_b64_tr_b16 v[176:177], v65 offset:0x1600
	ds_read_b64_tr_b16 v[178:179], v65 offset:0x1e00
	v_mfma_f32_32x32x16_bf16 v[32:47], v[74:77], v[180:183], v[32:47]
	ds_read_b64_tr_b16 v[180:181], v65 offset:0x2600
	ds_read_b64_tr_b16 v[182:183], v65 offset:0x2e00
	v_mfma_f32_32x32x16_bf16 v[32:47], v[78:81], v[190:193], v[32:47]
	ds_read_b64_tr_b16 v[190:191], v65 offset:0x3600
	ds_read_b64_tr_b16 v[192:193], v65 offset:0x3e00
	s_waitcnt lgkmcnt(8)
	v_mfma_f32_32x32x16_bf16 v[16:31], v[66:69], v[82:85], v[16:31]
	s_waitcnt lgkmcnt(0)
	v_mfma_f32_32x32x16_bf16 v[16:31], v[70:73], v[86:89], v[16:31]
	v_mfma_f32_32x32x16_bf16 v[16:31], v[74:77], v[90:93], v[16:31]
	v_mfma_f32_32x32x16_bf16 v[16:31], v[78:81], v[168:171], v[16:31]
	v_mfma_f32_32x32x16_bf16 v[0:15], v[66:69], v[172:175], v[0:15]
	s_waitcnt vmcnt(0)
	s_add_i32 s34, s34, 64
	s_cmp_eq_u32 s31, 32
	s_waitcnt vmcnt(0) lgkmcnt(0)
	s_barrier
	s_and_b32 s1, s31, 1
	s_mul_i32 s1, s1, 0x6000
	v_add3_u32 v156, v161, v162, s1
	ds_read_b128 v[236:239], v156 offset:0
	ds_read_b128 v[240:243], v156 offset:0x3000
	s_cmp_eq_u32 s31, 32
	v_mfma_f32_32x32x16_bf16 v[0:15], v[70:73], v[176:179], v[0:15]
	v_mfma_f32_32x32x16_bf16 v[0:15], v[74:77], v[180:183], v[0:15]
	v_mfma_f32_32x32x16_bf16 v[0:15], v[78:81], v[190:193], v[0:15]
	s_cbranch_scc1 .LBB0_185
	v_mov_b32_e32 v168, v64
	s_and_b32 s35, s31, 1
	s_cmp_eq_u32 s31, 31
	s_cbranch_scc0 .LBB0_170
	s_branch .LBB0_171
